# v94 + finalnorm: final-norm row loop reads its seven reloaded gain vectors from registers loaded once before the loop (no store/load round trip per multiply)
# baseline (speedup 1.0000x reference)
.LBB0_2389:
	v_readlane_b32 s2, v255, 15
	s_cmp_ge_i32 s2, s82
	s_cselect_b64 s[2:3], -1, 0
	s_and_b64 s[4:5], s[2:3], s[10:11]
	s_andn2_b64 vcc, exec, s[4:5]
	s_cbranch_vccnz .LBB0_2393
	v_readlane_b32 s6, v254, 0
	v_mov_b32_e32 v1, v0
	s_mov_b32 s7, 0
	s_lshl_b32 s6, s6, 3
	v_readfirstlane_b32 s4, v1
	s_ashr_i32 s5, s4, 6
	s_add_i32 s4, s5, s6
	s_cmpk_lt_i32 s4, 0x2080
	s_cbranch_scc0 .LBB0_2393
	s_waitcnt vmcnt(0)
	v_and_b32_e32 v20, 63, v1
	v_and_b32_e32 v1, 64, v226
	v_add_u32_e32 v2, 64, v1
	v_xor_b32_e32 v1, 1, v226
	v_cmp_lt_i32_e32 vcc, v1, v2
	s_waitcnt lgkmcnt(0)
	v_xor_b32_e32 v3, 2, v226
	s_load_dwordx4 s[36:39], s[0:1], s7 offset:0x110
	s_nop 0
	s_load_dwordx2 s[0:1], s[0:1], s7 offset:0x58
	v_cndmask_b32_e32 v1, v226, v1, vcc
	v_cmp_lt_i32_e32 vcc, v3, v2
	v_mov_b32_e32 v13, 0
	v_or_b32_e32 v22, 0x100, v20
	v_cndmask_b32_e32 v3, v226, v3, vcc
	v_lshlrev_b32_e32 v14, 2, v3
	v_xor_b32_e32 v3, 4, v226
	v_cmp_lt_i32_e32 vcc, v3, v2
	v_lshlrev_b32_e32 v12, 4, v20
	v_or_b32_e32 v24, 0x140, v20
	v_cndmask_b32_e32 v3, v226, v3, vcc
	v_lshlrev_b32_e32 v15, 2, v3
	v_xor_b32_e32 v3, 8, v226
	v_cmp_lt_i32_e32 vcc, v3, v2
	v_or_b32_e32 v26, 0x180, v20
	v_or_b32_e32 v28, 0x1c0, v20
	v_cndmask_b32_e32 v3, v226, v3, vcc
	v_lshlrev_b32_e32 v16, 2, v3
	v_xor_b32_e32 v3, 16, v226
	v_cmp_lt_i32_e32 vcc, v3, v2
	v_readlane_b32 s8, v255, 12
	v_readlane_b32 s9, v255, 13
	v_cndmask_b32_e32 v3, v226, v3, vcc
	v_lshlrev_b32_e32 v17, 2, v3
	v_xor_b32_e32 v3, 32, v226
	v_cmp_lt_i32_e32 vcc, v3, v2
	s_mov_b32 s11, 0
	v_lshlrev_b32_e32 v1, 2, v1
	v_cndmask_b32_e32 v2, v226, v3, vcc
	v_lshlrev_b32_e32 v18, 2, v2
	s_waitcnt lgkmcnt(0)
	v_lshl_add_u64 v[2:3], s[0:1], 0, v[12:13]
	v_lshlrev_b32_e32 v12, 4, v22
	v_lshl_add_u64 v[4:5], s[0:1], 0, v[12:13]
	v_lshlrev_b32_e32 v12, 4, v24
	v_lshl_add_u64 v[6:7], s[0:1], 0, v[12:13]
	v_lshlrev_b32_e32 v12, 4, v26
	v_lshl_add_u64 v[8:9], s[0:1], 0, v[12:13]
	v_lshlrev_b32_e32 v12, 4, v28
	v_lshl_add_u64 v[10:11], s[0:1], 0, v[12:13]
	s_ashr_i32 s0, s5, 31
	s_ashr_i32 s1, s6, 31
	s_add_u32 s6, s5, s6
	s_addc_u32 s7, s0, s1
	s_ashr_i32 s9, s8, 31
	s_lshl_b64 s[0:1], s[6:7], 11
	s_lshl_b64 s[12:13], s[8:9], 11
	s_lshl_b64 s[6:7], s[6:7], 12
	s_add_u32 s6, s38, s6
	v_lshlrev_b32_e32 v12, 3, v20
	s_addc_u32 s7, s39, s7
	v_lshl_add_u64 v[12:13], s[6:7], 0, v[12:13]
	s_mov_b64 s[6:7], 0x1de00800
	v_lshl_add_u64 v[12:13], v[12:13], 0, s[6:7]
	s_lshl_b64 s[14:15], s[8:9], 12
	v_mov_b32_e32 v19, 0x358637bd
	s_mov_b32 s5, 0x800000
	v_lshlrev_b32_e32 v20, 4, v20
	v_lshlrev_b32_e32 v21, 4, v22
	v_lshlrev_b32_e32 v22, 4, v24
	v_lshlrev_b32_e32 v23, 4, v26
	v_lshlrev_b32_e32 v24, 4, v28
	global_load_dwordx4 v[94:97], v[2:3], off offset:1024
	global_load_dwordx4 v[98:101], v[2:3], off offset:2048
	global_load_dwordx4 v[102:105], v[2:3], off offset:3072
	global_load_dwordx4 v[106:109], v[4:5], off
	global_load_dwordx4 v[110:113], v[6:7], off
	global_load_dwordx4 v[114:117], v[8:9], off
	global_load_dwordx4 v[118:121], v[10:11], off
.LBB0_2392:
	global_load_dwordx2 v[30:31], v[12:13], off offset:-2048
	global_load_dwordx2 v[32:33], v[12:13], off offset:-1536
	global_load_dwordx2 v[34:35], v[12:13], off offset:-1024
	global_load_dwordx2 v[36:37], v[12:13], off offset:-512
	global_load_dwordx2 v[38:39], v[12:13], off
	global_load_dwordx2 v[40:41], v[12:13], off offset:512
	global_load_dwordx2 v[42:43], v[12:13], off offset:1024
	global_load_dwordx2 v[44:45], v[12:13], off offset:1536
	global_load_dwordx4 v[26:29], v[2:3], off
	s_add_i32 s10, s4, 0xffffe000
	s_lshl_b64 s[6:7], s[10:11], 11
	s_add_u32 s6, s6, 0x1000000
	s_addc_u32 s7, s7, 0
	s_cmpk_lt_i32 s4, 0x2000
	s_cselect_b32 s7, s1, s7
	s_cselect_b32 s6, s0, s6
	s_lshl_b64 s[6:7], s[6:7], 2
	s_add_u32 s16, s36, s6
	s_addc_u32 s17, s37, s7
	s_add_i32 s4, s4, s8
	s_add_u32 s0, s0, s12
	s_addc_u32 s1, s1, s13
	v_lshl_add_u64 v[12:13], v[12:13], 0, s[14:15]
	s_cmpk_lt_i32 s4, 0x2080
	s_waitcnt vmcnt(8)
	v_lshlrev_b32_e32 v46, 16, v30
	v_and_b32_e32 v47, 0xffff0000, v30
	v_lshlrev_b32_e32 v30, 16, v31
	v_and_b32_e32 v31, 0xffff0000, v31
	s_waitcnt vmcnt(7)
	v_lshlrev_b32_e32 v49, 16, v33
	v_lshlrev_b32_e32 v48, 16, v32
	v_and_b32_e32 v33, 0xffff0000, v33
	v_and_b32_e32 v32, 0xffff0000, v32
	s_waitcnt vmcnt(5)
	v_lshlrev_b32_e32 v53, 16, v36
	v_and_b32_e32 v55, 0xffff0000, v36
	s_waitcnt vmcnt(2)
	v_and_b32_e32 v61, 0xffff0000, v42
	v_mul_f32_e32 v52, v31, v31
	v_mul_f32_e32 v54, v47, v47
	v_lshlrev_b32_e32 v50, 16, v34
	v_and_b32_e32 v51, 0xffff0000, v34
	v_lshlrev_b32_e32 v34, 16, v35
	v_and_b32_e32 v35, 0xffff0000, v35
	v_lshlrev_b32_e32 v60, 16, v42
	v_pk_mul_f32 v[66:67], v[32:33], v[32:33]
	v_mov_b32_e32 v69, v53
	v_mul_f32_e32 v68, v61, v61
	v_pk_fma_f32 v[76:77], v[30:31], v[30:31], v[52:53] op_sel_hi:[1,1,0]
	v_pk_fma_f32 v[78:79], v[46:47], v[46:47], v[54:55] op_sel_hi:[1,1,0]
	v_lshlrev_b32_e32 v36, 16, v37
	v_and_b32_e32 v37, 0xffff0000, v37
	s_waitcnt vmcnt(1)
	v_lshlrev_b32_e32 v63, 16, v44
	v_and_b32_e32 v65, 0xffff0000, v44
	v_mul_f32_e32 v62, v51, v51
	v_mul_f32_e32 v64, v35, v35
	v_pk_fma_f32 v[66:67], v[48:49], v[48:49], v[66:67]
	v_pk_fma_f32 v[84:85], v[60:61], v[60:61], v[68:69] op_sel_hi:[1,1,0]
	v_mov_b32_e32 v52, v78
	v_mov_b32_e32 v68, v76
	v_mul_f32_e32 v25, v55, v55
	v_mul_f32_e32 v88, v36, v36
	v_mul_f32_e32 v89, v37, v37
	v_pk_fma_f32 v[80:81], v[50:51], v[50:51], v[62:63] op_sel_hi:[1,1,0]
	v_pk_fma_f32 v[82:83], v[34:35], v[34:35], v[64:65] op_sel_hi:[1,1,0]
	v_pk_add_f32 v[76:77], v[78:79], v[76:77]
	v_pk_add_f32 v[66:67], v[66:67], v[66:67] op_sel:[0,1] op_sel_hi:[1,0]
	v_pk_mul_f32 v[68:69], v[52:53], v[68:69]
	v_lshlrev_b32_e32 v57, 16, v39
	v_lshlrev_b32_e32 v56, 16, v38
	v_and_b32_e32 v39, 0xffff0000, v39
	v_and_b32_e32 v38, 0xffff0000, v38
	v_mov_b32_e32 v81, v88
	v_mov_b32_e32 v83, v89
	v_mov_b32_e32 v67, v25
	v_mov_b32_e32 v77, v69
	v_pk_mul_f32 v[70:71], v[38:39], v[38:39]
	v_pk_add_f32 v[78:79], v[80:81], v[82:83]
	v_pk_add_f32 v[66:67], v[76:77], v[66:67]
	v_lshlrev_b32_e32 v59, 16, v41
	v_lshlrev_b32_e32 v58, 16, v40
	v_and_b32_e32 v41, 0xffff0000, v41
	v_and_b32_e32 v40, 0xffff0000, v40
	v_lshlrev_b32_e32 v42, 16, v43
	v_and_b32_e32 v43, 0xffff0000, v43
	v_pk_fma_f32 v[70:71], v[56:57], v[56:57], v[70:71]
	v_pk_add_f32 v[66:67], v[66:67], v[78:79]
	v_pk_mul_f32 v[72:73], v[40:41], v[40:41]
	v_mov_b32_e32 v75, v63
	v_mul_f32_e32 v74, v43, v43
	v_pk_add_f32 v[70:71], v[70:71], v[70:71] op_sel:[0,1] op_sel_hi:[1,0]
	v_pk_add_f32 v[66:67], v[66:67], v[66:67] op_sel:[0,1] op_sel_hi:[1,0]
	v_lshlrev_b32_e32 v44, 16, v45
	v_and_b32_e32 v45, 0xffff0000, v45
	v_pk_fma_f32 v[72:73], v[58:59], v[58:59], v[72:73]
	v_pk_fma_f32 v[86:87], v[42:43], v[42:43], v[74:75] op_sel_hi:[1,1,0]
	v_mov_b32_e32 v74, v70
	v_mov_b32_e32 v62, v66
	v_mul_f32_e32 v90, v65, v65
	v_mul_f32_e32 v91, v44, v44
	v_mul_f32_e32 v92, v45, v45
	v_pk_add_f32 v[72:73], v[72:73], v[72:73] op_sel:[0,1] op_sel_hi:[1,0]
	v_pk_add_f32 v[66:67], v[66:67], v[70:71]
	v_pk_mul_f32 v[68:69], v[62:63], v[74:75]
	v_mov_b32_e32 v85, v91
	v_mov_b32_e32 v87, v92
	v_mov_b32_e32 v73, v90
	v_mov_b32_e32 v67, v69
	v_pk_add_f32 v[80:81], v[84:85], v[86:87]
	v_pk_add_f32 v[66:67], v[66:67], v[72:73]
	v_mov_b32_e32 v54, v53
	v_pk_add_f32 v[66:67], v[66:67], v[80:81]
	v_mov_b32_e32 v64, v63
	v_add_f32_e32 v25, v66, v67
	ds_bpermute_b32 v52, v1, v25
	s_waitcnt lgkmcnt(0)
	v_add_f32_e32 v25, v25, v52
	ds_bpermute_b32 v52, v14, v25
	s_waitcnt lgkmcnt(0)
	v_add_f32_e32 v25, v25, v52
	ds_bpermute_b32 v52, v15, v25
	s_waitcnt lgkmcnt(0)
	v_add_f32_e32 v25, v25, v52
	ds_bpermute_b32 v52, v16, v25
	s_waitcnt lgkmcnt(0)
	v_add_f32_e32 v25, v25, v52
	ds_bpermute_b32 v52, v17, v25
	s_waitcnt lgkmcnt(0)
	v_add_f32_e32 v25, v25, v52
	ds_bpermute_b32 v52, v18, v25
	s_waitcnt lgkmcnt(0)
	v_add_f32_e32 v25, v25, v52
	v_fmamk_f32 v25, v25, 0x3a000000, v19
	v_mul_f32_e32 v52, 0x4b800000, v25
	v_cmp_gt_f32_e32 vcc, s5, v25
	s_nop 1
	v_cndmask_b32_e32 v25, v25, v52, vcc
	v_rsq_f32_e32 v25, v25
	s_nop 0
	v_mul_f32_e32 v52, 0x45800000, v25
	v_cndmask_b32_e32 v52, v25, v52, vcc
	v_pk_mul_f32 v[46:47], v[52:53], v[46:47] op_sel_hi:[0,1]
	v_pk_mul_f32 v[30:31], v[52:53], v[30:31] op_sel_hi:[0,1]
	s_waitcnt vmcnt(0)
	v_pk_mul_f32 v[28:29], v[30:31], v[28:29]
	v_pk_mul_f32 v[26:27], v[46:47], v[26:27]
	global_store_dwordx4 v20, v[26:29], s[16:17]
	v_mov_b32_e32 v30, v49
	v_mov_b32_e32 v31, v33
	v_mov_b32_e32 v49, v32
	v_pk_mul_f32 v[30:31], v[52:53], v[30:31] op_sel_hi:[0,1]
	v_pk_mul_f32 v[32:33], v[52:53], v[48:49] op_sel_hi:[0,1]
	v_pk_mul_f32 v[26:27], v[32:33], v[94:95]
	v_pk_mul_f32 v[28:29], v[30:31], v[96:97]
	global_store_dwordx4 v20, v[26:29], s[16:17] offset:1024
	v_pk_mul_f32 v[30:31], v[52:53], v[34:35] op_sel_hi:[0,1]
	v_pk_mul_f32 v[32:33], v[52:53], v[50:51] op_sel_hi:[0,1]
	v_pk_mul_f32 v[26:27], v[32:33], v[98:99]
	v_pk_mul_f32 v[28:29], v[30:31], v[100:101]
	global_store_dwordx4 v20, v[26:29], s[16:17] offset:2048
	v_pk_mul_f32 v[30:31], v[52:53], v[36:37] op_sel_hi:[0,1]
	v_pk_mul_f32 v[32:33], v[52:53], v[54:55] op_sel_hi:[0,1]
	v_pk_mul_f32 v[26:27], v[32:33], v[102:103]
	v_pk_mul_f32 v[28:29], v[30:31], v[104:105]
	global_store_dwordx4 v20, v[26:29], s[16:17] offset:3072
	v_mov_b32_e32 v30, v57
	v_mov_b32_e32 v31, v39
	v_mov_b32_e32 v57, v38
	v_pk_mul_f32 v[30:31], v[52:53], v[30:31] op_sel_hi:[0,1]
	v_pk_mul_f32 v[32:33], v[52:53], v[56:57] op_sel_hi:[0,1]
	v_pk_mul_f32 v[26:27], v[32:33], v[106:107]
	v_pk_mul_f32 v[28:29], v[30:31], v[108:109]
	global_store_dwordx4 v21, v[26:29], s[16:17]
	v_mov_b32_e32 v30, v59
	v_mov_b32_e32 v31, v41
	v_mov_b32_e32 v59, v40
	v_pk_mul_f32 v[30:31], v[52:53], v[30:31] op_sel_hi:[0,1]
	v_pk_mul_f32 v[32:33], v[52:53], v[58:59] op_sel_hi:[0,1]
	v_pk_mul_f32 v[26:27], v[32:33], v[110:111]
	v_pk_mul_f32 v[28:29], v[30:31], v[112:113]
	global_store_dwordx4 v22, v[26:29], s[16:17]
	v_pk_mul_f32 v[30:31], v[52:53], v[42:43] op_sel_hi:[0,1]
	v_pk_mul_f32 v[32:33], v[52:53], v[60:61] op_sel_hi:[0,1]
	v_pk_mul_f32 v[26:27], v[32:33], v[114:115]
	v_pk_mul_f32 v[28:29], v[30:31], v[116:117]
	global_store_dwordx4 v23, v[26:29], s[16:17]
	v_pk_mul_f32 v[30:31], v[52:53], v[44:45] op_sel_hi:[0,1]
	v_pk_mul_f32 v[32:33], v[52:53], v[64:65] op_sel_hi:[0,1]
	v_pk_mul_f32 v[26:27], v[32:33], v[118:119]
	v_pk_mul_f32 v[28:29], v[30:31], v[120:121]
	global_store_dwordx4 v24, v[26:29], s[16:17]
	s_cbranch_scc1 .LBB0_2392
